# P2: sample-attention workgroups take one GLA unit, others exactly five (plus seam edits)
# speedup vs baseline: 1.0071x; 1.0000x over previous
; #define LAS __attribute__((address_space(3)))
; template <int MODE, bool dry = false>
; __device__ __forceinline__ void gla_unit(const Args& a, LAS unsigned char* lds, int idx, int h, int tid, const float (&wu)[16], float bd) {
;     constexpr int C = (MODE == 2) ? 32 : 64, TPT = C / 4, NTL = C / 16, KS_T = C / 32;
;     const int lane = tid & 63, wave = __builtin_amdgcn_readfirstlane(tid >> 6), fr = lane & 15, kq = lane >> 4;
;     LAS bf16_t* qe = (LAS bf16_t*)(lds + G_QE); LAS bf16_t* ke = (LAS bf16_t*)(lds + G_KE); LAS bf16_t* klT = (LAS bf16_t*)(lds + G_KLT);
;     LAS bf16_t* vT = (LAS bf16_t*)(lds + G_VT); LAS bf16_t* att = (LAS bf16_t*)(lds + G_ATT);
;     LAS float* psum = (LAS float*)(lds + G_PSUM); LAS float* blast = (LAS float*)(lds + G_BLAST); LAS float* dvec = (LAS float*)(lds + G_DVEC); LAS float* red = (LAS float*)(lds + G_RED);
;     const int row0 = (MODE == 2) ? MP + idx * 32 : idx * 64;
;     const bf16_t* QB = (const bf16_t*)(a.ws + A_QB); const bf16_t* KB = (const bf16_t*)(a.ws + A_KB); bf16_t* VB = (bf16_t*)(a.ws + A_VB); const bf16_t* RB = (const bf16_t*)(a.ws + A_RB);
;     const float* DLR = (const float*)((const unsigned char*)a.out + Y_DLR);
;     bf16_t* US = (bf16_t*)((unsigned char*)a.out + Y_US) + (size_t)(idx * 4 + h) * 32768;
;     bf16x8 vraw[C / 16];
;     { const int t = tid & (C - 1), g0 = tid / C;
; #pragma unroll
;         for (int gi = 0; gi < C / 16; ++gi) vraw[gi] = *(const bf16x8*)(VB + (size_t)(row0 + t) * 1024 + h * 256 + 8 * (g0 * (C / 16) + gi)); }
; __global__ void __launch_bounds__(512) fwd_kernel(Args a) {
;     ...
;         GLA_HEAD_CONSTS(bx & 3);
;         const bool few = (G == 256) && bx < 32;
;         for (int u = (G != 256) ? bx : (few ? bx : 64 + bx - 32); u < (few ? 64 : 1024 + 128); u += (G != 256) ? G : (few ? 32 : 224)) {
;             if ((G & 3) != 0) { const int col_ = (u & 3) * 128 + (tid & 127); for (int j = 0; j < 16; ++j) wu_[j] = a.in[I_WUP][j * 512 + col_]; }
;             const float bdu = (G & 3) ? a.in[I_BDEC][(u & 3) * 128 + (tid & 127)] : bd_;
;             if (u < 1024) gla_unit<0>(a, lds, u >> 2, u & 3, tid, wu_, bdu);
;             else gla_unit<2>(a, lds, (u - 1024) >> 2, u & 3, tid, wu_, bdu); }
.LBB0_521:
	s_add_i32 s3, s2, 0
	s_cmp_lt_i32 s2, 32
	s_cselect_b64 s[8:9], -1, 0
	s_and_b64 s[0:1], s[8:9], exec
	s_cselect_b32 s3, s2, s3
	s_cmpk_eq_i32 s58, 0x100
	s_cselect_b64 s[10:11], -1, 0
	s_and_b64 s[0:1], s[10:11], exec
	s_cselect_b32 s24, s3, s2
	s_and_b64 s[0:1], s[8:9], s[10:11]
	s_and_b64 s[0:1], s[0:1], exec
	s_cselect_b32 s71, 32, 0x480
	s_cmp_lt_i32 s24, s71
	s_movk_i32 s3, 0x100
	s_barrier
	s_cbranch_scc0 .LBB0_545
	s_lshl_b32 s0, s2, 7
	s_and_b32 s0, s0, 0x180
	v_and_b32_e32 v37, 0x7f, v178
	v_or_b32_e32 v0, s0, v37
	v_lshlrev_b32_e32 v32, 2, v0
	v_mov_b32_e32 v33, 0
	v_lshl_add_u64 v[10:11], s[16:17], 0, v[32:33]
	s_movk_i32 s72, 0x1000
	s_add_i32 s0, 0, 0x18400
	v_lshlrev_b32_e32 v3, 2, v37
	v_add_co_u32_e32 v14, vcc, s72, v10
	v_add_u32_e32 v39, s0, v3
	s_nop 0
	v_addc_co_u32_e32 v15, vcc, 0, v11, vcc
	s_movk_i32 s0, 0x2000
	v_add_co_u32_e32 v12, vcc, s0, v10
	s_movk_i32 s0, 0x3000
	s_nop 0
	v_addc_co_u32_e32 v13, vcc, 0, v11, vcc
	v_add_co_u32_e32 v16, vcc, s0, v10
	s_movk_i32 s0, 0x4000
	s_nop 0
	v_addc_co_u32_e32 v17, vcc, 0, v11, vcc
	v_add_co_u32_e32 v18, vcc, s0, v10
	s_movk_i32 s0, 0x5000
	s_nop 0
	v_addc_co_u32_e32 v19, vcc, 0, v11, vcc
	v_add_co_u32_e32 v20, vcc, s0, v10
	s_movk_i32 s0, 0x6000
	s_nop 0
	v_addc_co_u32_e32 v21, vcc, 0, v11, vcc
	v_add_co_u32_e32 v22, vcc, s0, v10
	s_movk_i32 s0, 0x7000
	s_nop 0
	v_addc_co_u32_e32 v23, vcc, 0, v11, vcc
	v_add_co_u32_e32 v24, vcc, s0, v10
	s_and_b32 s0, s58, 3
	s_cmp_lg_u32 s0, 0
	s_cselect_b64 s[28:29], -1, 0
	s_add_u32 s30, s54, 0x5600000
	s_addc_u32 s31, s55, 0
	s_add_u32 s34, s54, 0x7800000
	global_load_dword v51, v32, s[18:19]
	global_load_dword v0, v32, s[16:17]
	global_load_dword v1, v32, s[16:17] offset:2048
	global_load_dword v2, v[12:13], off offset:-4096
	global_load_dword v4, v[12:13], off
	global_load_dword v5, v[12:13], off offset:2048
	global_load_dword v6, v[18:19], off offset:-4096
	global_load_dword v8, v[18:19], off
	s_addc_u32 s35, s55, 0
	v_lshlrev_b32_e32 v32, 4, v178
	v_lshrrev_b32_e32 v7, 1, v178
	v_bfe_u32 v9, v178, 4, 2
	s_add_u32 s90, s54, 0x6700000
	v_lshl_add_u64 v[12:13], s[52:53], 0, v[32:33]
	s_mov_b64 s[4:5], 0x4000000
	s_addc_u32 s91, s55, 0
	v_lshl_add_u64 v[34:35], v[12:13], 0, s[4:5]
	s_add_i32 s4, 0, 0x19800
	s_add_i32 s25, 0, 0x18e00
	v_or_b32_e32 v12, 15, v7
	v_lshlrev_b32_e32 v61, 2, v9
	v_mul_u32_u24_e32 v27, 0x90, v12
	v_lshlrev_b32_e32 v62, 3, v9
	v_lshlrev_b32_e32 v28, 4, v9
	s_add_u32 s74, s52, 0x4a80000
	v_lshlrev_b32_e32 v12, 11, v9
	v_cmp_eq_u32_e64 s[6:7], 0, v9
	v_lshlrev_b32_e32 v68, 10, v9
	v_or_b32_e32 v9, 16, v61
	v_lshl_add_u32 v58, v178, 4, s4
	s_addc_u32 s75, s53, 0
	s_add_i32 s4, 0, 0x16000
	v_lshl_add_u32 v72, v9, 2, s25
	v_lshlrev_b32_e32 v73, 8, v9
	v_or_b32_e32 v9, 32, v61
	v_add_u32_e32 v30, s4, v28
	s_add_i32 s4, 0, 0x19000
	v_lshl_add_u32 v77, v9, 2, s25
	v_lshlrev_b32_e32 v78, 8, v9
	v_or_b32_e32 v9, 48, v61
	v_writelane_b32 v252, s93, 17
	s_mov_b32 s93, s94
	s_add_u32 s94, s54, 0x9a00000
	v_lshl_add_u32 v82, v9, 2, s25
	v_lshlrev_b32_e32 v83, 8, v9
	v_or_b32_e32 v9, 64, v61
	v_and_b32_e32 v57, 15, v178
	s_addc_u32 s95, s55, 0
	v_lshl_add_u32 v87, v9, 2, s25
	v_lshlrev_b32_e32 v88, 8, v9
	v_or_b32_e32 v9, 0x50, v61
	v_or_b32_e32 v64, 16, v57
	s_and_b64 s[8:9], s[8:9], exec
	v_lshl_add_u32 v92, v9, 2, s25
	v_lshlrev_b32_e32 v93, 8, v9
	v_or_b32_e32 v9, 0x60, v61
	v_lshl_add_u32 v65, v57, 2, s4
	v_lshl_add_u32 v66, v64, 2, s4
	v_cmp_gt_u32_e64 s[4:5], s3, v178
	s_cselect_b32 s3, 32, 0xe0
	s_and_b64 s[8:9], s[10:11], exec
	v_lshl_add_u32 v97, v9, 2, s25
	v_lshlrev_b32_e32 v98, 8, v9
	v_or_b32_e32 v9, 0x70, v61
	v_add_u32_e32 v59, s25, v3
	s_cselect_b32 s96, s3, s58
	v_add_u32_e32 v67, s25, v28
	v_lshl_add_u32 v102, v9, 2, s25
	s_ashr_i32 s25, s24, 31
	v_and_b32_e32 v56, 31, v178
	v_and_b32_e32 v10, 0x1f0, v7
	v_and_b32_e32 v26, 0x1e0, v7
	v_or_b32_e32 v7, 31, v7
	s_lshl_b64 s[8:9], s[24:25], 9
	v_addc_co_u32_e32 v25, vcc, 0, v11, vcc
	v_lshl_add_u32 v11, v56, 1, 0
	v_mul_u32_u24_e32 v13, 0x90, v10
	v_add_u32_e32 v36, 0, v28
	v_lshl_add_u32 v32, v176, 1, 0
	v_mul_u32_u24_e32 v7, 0x90, v7
	v_or_b32_e32 v28, s8, v3
	v_mbcnt_lo_u32_b32 v3, -1, 0
	v_lshlrev_b32_e32 v103, 8, v9
	v_lshlrev_b32_e32 v44, 1, v10
	v_add_u32_e32 v107, v11, v13
	v_add_u32_e32 v108, v11, v27
	v_lshlrev_b32_e32 v46, 2, v12
	v_add_u32_e32 v112, v32, v7
	v_mbcnt_hi_u32_b32 v114, -1, v3
	global_load_dword v9, v[18:19], off offset:2048
	global_load_dword v10, v[22:23], off offset:-4096
	global_load_dword v12, v[22:23], off
	global_load_dword v13, v[22:23], off offset:2048
	global_load_dword v3, v[14:15], off offset:2048
	global_load_dword v7, v[16:17], off offset:2048
	global_load_dword v11, v[20:21], off offset:2048
	s_nop 0
	global_load_dword v14, v[24:25], off
	global_load_dword v15, v[24:25], off offset:2048
	v_and_b32_e32 v29, 48, v178
	v_add_u32_e32 v38, 0, v29
	v_mov_b32_e32 v29, s9
	s_mov_b64 s[8:9], 0x4110000
	s_movk_i32 s0, 0x80
	s_movk_i32 s73, 0x90
	v_mul_u32_u24_e32 v63, 0x90, v57
	v_mul_u32_u24_e32 v31, 0x110, v57
	v_mul_u32_u24_e32 v45, 0x90, v26
	v_lshl_add_u64 v[40:41], v[28:29], 0, s[8:9]
	s_ashr_i32 s97, s96, 31
	s_lshl_b64 s[8:9], s[24:25], 16
	s_mov_b32 s33, s81
	s_mov_b32 s27, 0
	v_cmp_gt_u32_e64 s[0:1], s0, v178
	v_mad_u32_u24 v60, v37, s73, 0
	s_movk_i32 s76, 0x110
	v_or_b32_e32 v69, 0x100, v68
	v_or_b32_e32 v70, 0x200, v68
	v_or_b32_e32 v71, 0x300, v68
	v_or_b32_e32 v74, 0x1100, v68
	v_or_b32_e32 v75, 0x1200, v68
	v_or_b32_e32 v76, 0x1300, v68
	v_or_b32_e32 v79, 0x2100, v68
	v_or_b32_e32 v80, 0x2200, v68
	v_or_b32_e32 v81, 0x2300, v68
	v_or_b32_e32 v84, 0x3100, v68
	v_or_b32_e32 v85, 0x3200, v68
	v_or_b32_e32 v86, 0x3300, v68
	v_or_b32_e32 v89, 0x4100, v68
	v_or_b32_e32 v90, 0x4200, v68
	v_or_b32_e32 v91, 0x4300, v68
	v_or_b32_e32 v94, 0x5100, v68
	v_or_b32_e32 v95, 0x5200, v68
	v_or_b32_e32 v96, 0x5300, v68
	v_or_b32_e32 v99, 0x6100, v68
	v_or_b32_e32 v100, 0x6200, v68
	v_or_b32_e32 v101, 0x6300, v68
	v_or_b32_e32 v104, 0x7100, v68
	v_or_b32_e32 v105, 0x7200, v68
	v_or_b32_e32 v106, 0x7300, v68
	s_lshl_b32 s77, s24, 4
	s_lshl_b32 s78, s96, 4
	s_lshl_b64 s[60:61], s[96:97], 9
	s_lshl_b32 s79, s24, 7
	s_lshl_b32 s80, s96, 7
	v_or_b32_e32 v42, s8, v62
	v_mov_b32_e32 v43, s9
	s_lshl_b64 s[62:63], s[96:97], 16
	s_mov_b32 s25, 0xbfb8aa3b
	s_mov_b32 s92, 0x800000
	s_mov_b32 s81, 0x3f317217
	s_mov_b32 s82, 0x7f800000
	s_mov_b32 s83, 0x3d800000
	v_add_u32_e32 v109, v30, v63
	v_add_u32_e32 v110, v36, v31
	s_mov_b64 s[64:65], 0x8000
	s_mov_b64 s[66:67], 0x10000
	s_mov_b64 s[68:69], 0x18000
	s_mov_b32 s70, 0x3b800000
	v_lshlrev_b32_e32 v48, 1, v26
	v_add_u32_e32 v111, v32, v45
	v_mov_b32_e32 v113, 0x41b17218
	v_mov_b32_e32 v50, 0x358637bd
	s_branch .LBB0_525
